# v21 plus counted LDS waits at the PV start (lgkmcnt 14/12/10/8 in front of the first four PV MFMAs instead of one lgkmcnt(8)) in the attention loops
# speedup vs baseline: 1.0009x; 1.0009x over previous
; #define FA_SBAR() __builtin_amdgcn_sched_barrier(0)
; #define FA_RD8(S, d0) do { constexpr int b_ = v_rd_off(d0, 0, 0); FA_TRRD(S##l0, b_); FA_TRRD(S##h0, b_ + 2048); FA_TRRD(S##l1, b_ + 4096); FA_TRRD(S##h1, b_ + 6144); FA_TRRD(S##l2, b_ + 8192); FA_TRRD(S##h2, b_ + 10240); FA_TRRD(S##l3, b_ + 12288); FA_TRRD(S##h3, b_ + 14336); } while (0)
; __device__ __forceinline__ void partialSM(f32x16& p0, f32x16& p1, float& m_reg, float& mn, float& alpha, const float sc, const float C2) {
;     ...
;     const float mnL = -mn * C2;
; #pragma unroll
;     for (int r = 0; r < 16; ++r) p0[r] = __builtin_amdgcn_exp2f(fmaf(p0[r], C2, mnL));
; #pragma unroll
;     for (int r = 0; r < 16; ++r) p1[r] = __builtin_amdgcn_exp2f(fmaf(p1[r], C2, mnL));
; }
; __device__ __forceinline__ void finishSM(const f32x16& p0, const f32x16& p1, float alpha, float& l_reg, half8& pa0, half8& pa1, half8& pa2, half8& pa3) {
;     f32x2 s2 = {0.f, 0.f};
; #pragma unroll
;     for (int r = 0; r < 16; r += 2) { s2 += (f32x2){p0[r], p0[r + 1]}; s2 += (f32x2){p1[r], p1[r + 1]}; }
;     float ps = s2[0] + s2[1];
;     { auto rr = __builtin_amdgcn_permlane32_swap(__float_as_uint(ps), __float_as_uint(ps), false, false);
;       ps = __uint_as_float(rr[0]) + __uint_as_float(rr[1]); }
;     l_reg = l_reg * alpha + ps;
;     ...
;     FA_PK4(p0, 0, pa0); FA_PK4(p0, 8, pa1); FA_PK4(p1, 0, pa2); FA_PK4(p1, 8, pa3);
; __device__ __forceinline__ void pv_tile2(f32x16* o, int vb0, half8 pa0, half8 pa1, half8 pa2, half8 pa3) {
;     ...
;     s16x4 al0, al1, al2, al3, ah0, ah1, ah2, ah3, bl0, bl1, bl2, bl3, bh0, bh1, bh2, bh3;
;     FA_RD8(a, 0);
;     FA_RD8(b, 1); asm volatile("s_waitcnt lgkmcnt(8)" ::: "memory"); FA_SBAR(); FA_MM4(a, 0); FA_SBAR();
;     FA_RD8(a, 2); asm volatile("s_waitcnt lgkmcnt(8)" ::: "memory"); FA_SBAR(); FA_MM4(b, 1); FA_SBAR();
;     FA_RD8(b, 3); asm volatile("s_waitcnt lgkmcnt(8)" ::: "memory"); FA_SBAR(); FA_MM4(a, 2); FA_SBAR();
;     asm volatile("s_waitcnt lgkmcnt(0)" ::: "memory"); FA_SBAR(); FA_MM4(b, 3);
.LBB0_4821:
	v_mul_f32_e32 v183, 0xbe0293ee, v181
	v_fmamk_f32 v97, v98, 0x3e0293ee, v183
	v_fmamk_f32 v84, v84, 0x3e0293ee, v183
	v_exp_f32_e32 v98, v97
	v_fmamk_f32 v97, v99, 0x3e0293ee, v183
	v_exp_f32_e32 v103, v84
	v_fmamk_f32 v84, v101, 0x3e0293ee, v183
	v_exp_f32_e32 v99, v97
	v_fmamk_f32 v97, v100, 0x3e0293ee, v183
	v_exp_f32_e32 v100, v84
	v_fmamk_f32 v84, v86, 0x3e0293ee, v183
	v_exp_f32_e32 v101, v84
	v_fmamk_f32 v84, v87, 0x3e0293ee, v183
	v_exp_f32_e32 v86, v84
	v_fmamk_f32 v84, v88, 0x3e0293ee, v183
	v_exp_f32_e32 v87, v84
	v_fmamk_f32 v84, v89, 0x3e0293ee, v183
	v_exp_f32_e32 v88, v84
	v_fmamk_f32 v84, v90, 0x3e0293ee, v183
	v_exp_f32_e32 v89, v84
	v_fmamk_f32 v84, v91, 0x3e0293ee, v183
	v_exp_f32_e32 v90, v84
	v_fmamk_f32 v84, v92, 0x3e0293ee, v183
	v_exp_f32_e32 v91, v84
	v_fmamk_f32 v84, v93, 0x3e0293ee, v183
	v_exp_f32_e32 v92, v84
	v_fmamk_f32 v84, v94, 0x3e0293ee, v183
	v_exp_f32_e32 v93, v84
	v_fmamk_f32 v84, v95, 0x3e0293ee, v183
	v_fmamk_f32 v4, v4, 0x3e0293ee, v183
	v_exp_f32_e32 v94, v84
	v_fmamk_f32 v84, v96, 0x3e0293ee, v183
	v_exp_f32_e32 v96, v4
	v_fmamk_f32 v4, v5, 0x3e0293ee, v183
	v_exp_f32_e32 v102, v97
	v_exp_f32_e32 v97, v4
	v_fmamk_f32 v4, v6, 0x3e0293ee, v183
	v_exp_f32_e32 v104, v4
	v_fmamk_f32 v4, v7, 0x3e0293ee, v183
	v_exp_f32_e32 v105, v4
	v_fmamk_f32 v4, v8, 0x3e0293ee, v183
	v_exp_f32_e32 v106, v4
	v_fmamk_f32 v4, v9, 0x3e0293ee, v183
	v_exp_f32_e32 v107, v4
	v_fmamk_f32 v4, v10, 0x3e0293ee, v183
	v_exp_f32_e32 v108, v4
	v_fmamk_f32 v4, v11, 0x3e0293ee, v183
	v_exp_f32_e32 v109, v4
	v_fmamk_f32 v4, v12, 0x3e0293ee, v183
	v_exp_f32_e32 v110, v4
	v_fmamk_f32 v4, v13, 0x3e0293ee, v183
	v_exp_f32_e32 v111, v4
	v_fmamk_f32 v4, v14, 0x3e0293ee, v183
	v_exp_f32_e32 v112, v4
	v_fmamk_f32 v4, v15, 0x3e0293ee, v183
	v_exp_f32_e32 v113, v4
	v_fmamk_f32 v4, v16, 0x3e0293ee, v183
	v_exp_f32_e32 v16, v4
	v_fmamk_f32 v4, v17, 0x3e0293ee, v183
	v_exp_f32_e32 v17, v4
	v_fmamk_f32 v4, v82, 0x3e0293ee, v183
	v_exp_f32_e32 v184, v4
	v_pk_add_f32 v[4:5], v[98:99], 0 op_sel_hi:[1,0]
	v_exp_f32_e32 v95, v84
	v_pk_add_f32 v[4:5], v[96:97], v[4:5]
	v_fmac_f32_e32 v183, 0x3e0293ee, v83
	v_pk_add_f32 v[4:5], v[102:103], v[4:5]
	v_exp_f32_e32 v185, v183
	v_pk_add_f32 v[4:5], v[104:105], v[4:5]
	v_cvt_pk_f16_f32 v6, v100, v101
	v_pk_add_f32 v[4:5], v[100:101], v[4:5]
	v_cvt_pk_f16_f32 v7, v86, v87
	v_pk_add_f32 v[4:5], v[106:107], v[4:5]
	v_cvt_pk_f16_f32 v8, v88, v89
	v_pk_add_f32 v[4:5], v[86:87], v[4:5]
	v_cvt_pk_f16_f32 v9, v90, v91
	v_pk_add_f32 v[4:5], v[108:109], v[4:5]
	v_cvt_pk_f16_f32 v10, v92, v93
	v_pk_add_f32 v[4:5], v[88:89], v[4:5]
	v_cvt_pk_f16_f32 v11, v94, v95
	v_pk_add_f32 v[4:5], v[110:111], v[4:5]
	v_cvt_pk_f16_f32 v12, v96, v97
	v_pk_add_f32 v[4:5], v[90:91], v[4:5]
	v_cvt_pk_f16_f32 v13, v104, v105
	v_pk_add_f32 v[4:5], v[112:113], v[4:5]
	v_cvt_pk_f16_f32 v14, v106, v107
	v_pk_add_f32 v[4:5], v[92:93], v[4:5]
	v_cvt_pk_f16_f32 v15, v108, v109
	v_pk_add_f32 v[4:5], v[16:17], v[4:5]
	v_cvt_pk_f16_f32 v82, v110, v111
	v_pk_add_f32 v[4:5], v[94:95], v[4:5]
	v_cvt_pk_f16_f32 v83, v112, v113
	v_pk_add_f32 v[4:5], v[184:185], v[4:5]
	v_cvt_pk_f16_f32 v84, v16, v17
	v_pk_add_f32 v[4:5], v[4:5], v[4:5] op_sel:[0,1] op_sel_hi:[1,0]
	v_permlane32_swap_b32_e32 v8, v10
	v_mov_b32_e32 v5, v4
	s_nop 1
	v_permlane32_swap_b32_e32 v4, v5
	v_add_f32_e32 v188, v4, v5
	v_fmac_f32_e32 v188, v182, v85
	v_cvt_pk_f16_f32 v4, v98, v99
	v_cvt_pk_f16_f32 v5, v102, v103
	v_cvt_pk_f16_f32 v85, v184, v185
	v_permlane32_swap_b32_e32 v4, v6
	v_permlane32_swap_b32_e32 v5, v7
	v_permlane32_swap_b32_e32 v9, v11
	v_permlane32_swap_b32_e32 v12, v14
	v_permlane32_swap_b32_e32 v13, v15
	v_permlane32_swap_b32_e32 v82, v84
	v_permlane32_swap_b32_e32 v83, v85
	v_add_u32_e32 v2, v179, v2
	ds_read_b64_tr_b16 v[86:87], v2 offset:0
	ds_read_b64_tr_b16 v[88:89], v2 offset:0x800
	ds_read_b64_tr_b16 v[90:91], v2 offset:0x1000
	ds_read_b64_tr_b16 v[92:93], v2 offset:0x1800
	ds_read_b64_tr_b16 v[94:95], v2 offset:0x2000
	ds_read_b64_tr_b16 v[96:97], v2 offset:0x2800
	ds_read_b64_tr_b16 v[98:99], v2 offset:0x3000
	ds_read_b64_tr_b16 v[100:101], v2 offset:0x3800
	ds_read_b64_tr_b16 v[102:103], v2 offset:0x200
	ds_read_b64_tr_b16 v[104:105], v2 offset:0xa00
	ds_read_b64_tr_b16 v[106:107], v2 offset:0x1200
	ds_read_b64_tr_b16 v[108:109], v2 offset:0x1a00
	ds_read_b64_tr_b16 v[110:111], v2 offset:0x2200
	ds_read_b64_tr_b16 v[112:113], v2 offset:0x2a00
	ds_read_b64_tr_b16 v[182:183], v2 offset:0x3200
	ds_read_b64_tr_b16 v[184:185], v2 offset:0x3a00
	s_waitcnt lgkmcnt(14)
	s_nop 0
	v_mfma_f32_32x32x16_f16 v[66:81], v[4:7], v[86:89], v[66:81]
	s_waitcnt lgkmcnt(12)
	v_mfma_f32_32x32x16_f16 v[66:81], v[8:11], v[90:93], v[66:81]
	s_waitcnt lgkmcnt(10)
	v_mfma_f32_32x32x16_f16 v[66:81], v[12:15], v[94:97], v[66:81]
	s_waitcnt lgkmcnt(8)
	v_mfma_f32_32x32x16_f16 v[66:81], v[82:85], v[98:101], v[66:81]
	ds_read_b64_tr_b16 v[86:87], v2 offset:0x400
	ds_read_b64_tr_b16 v[88:89], v2 offset:0xc00
	ds_read_b64_tr_b16 v[90:91], v2 offset:0x1400
	ds_read_b64_tr_b16 v[92:93], v2 offset:0x1c00
	ds_read_b64_tr_b16 v[94:95], v2 offset:0x2400
	ds_read_b64_tr_b16 v[96:97], v2 offset:0x2c00
	ds_read_b64_tr_b16 v[98:99], v2 offset:0x3400
	ds_read_b64_tr_b16 v[100:101], v2 offset:0x3c00
	s_waitcnt lgkmcnt(8)
	v_mfma_f32_32x32x16_f16 v[50:65], v[4:7], v[102:105], v[50:65]
	v_mfma_f32_32x32x16_f16 v[50:65], v[8:11], v[106:109], v[50:65]
	v_mfma_f32_32x32x16_f16 v[50:65], v[12:15], v[110:113], v[50:65]
	v_mfma_f32_32x32x16_f16 v[50:65], v[82:85], v[182:185], v[50:65]
	ds_read_b64_tr_b16 v[102:103], v2 offset:0x600
	ds_read_b64_tr_b16 v[104:105], v2 offset:0xe00
	ds_read_b64_tr_b16 v[106:107], v2 offset:0x1600
	ds_read_b64_tr_b16 v[108:109], v2 offset:0x1e00
	ds_read_b64_tr_b16 v[110:111], v2 offset:0x2600
	ds_read_b64_tr_b16 v[112:113], v2 offset:0x2e00
	ds_read_b64_tr_b16 v[184:185], v2 offset:0x3600
	ds_read_b64_tr_b16 v[186:187], v2 offset:0x3e00
	s_waitcnt lgkmcnt(8)
	v_mfma_f32_32x32x16_f16 v[34:49], v[4:7], v[86:89], v[34:49]
	v_mfma_f32_32x32x16_f16 v[34:49], v[8:11], v[90:93], v[34:49]
	v_mfma_f32_32x32x16_f16 v[34:49], v[12:15], v[94:97], v[34:49]
	v_mfma_f32_32x32x16_f16 v[34:49], v[82:85], v[98:101], v[34:49]
	s_waitcnt lgkmcnt(0)
	v_mfma_f32_32x32x16_f16 v[18:33], v[4:7], v[102:105], v[18:33]
	v_mov_b32_e32 v182, v188
	v_mfma_f32_32x32x16_f16 v[18:33], v[8:11], v[106:109], v[18:33]
	v_mfma_f32_32x32x16_f16 v[18:33], v[12:15], v[110:113], v[18:33]
	v_mfma_f32_32x32x16_f16 v[18:33], v[82:85], v[184:187], v[18:33]

; #define FA_SBAR() __builtin_amdgcn_sched_barrier(0)
; #define FA_RD8(S, d0) do { constexpr int b_ = v_rd_off(d0, 0, 0); FA_TRRD(S##l0, b_); FA_TRRD(S##h0, b_ + 2048); FA_TRRD(S##l1, b_ + 4096); FA_TRRD(S##h1, b_ + 6144); FA_TRRD(S##l2, b_ + 8192); FA_TRRD(S##h2, b_ + 10240); FA_TRRD(S##l3, b_ + 12288); FA_TRRD(S##h3, b_ + 14336); } while (0)
; __device__ __forceinline__ void partialSM(f32x16& p0, f32x16& p1, float& m_reg, float& mn, float& alpha, const float sc, const float C2) {
;     ...
;     const float mnL = -mn * C2;
; #pragma unroll
;     for (int r = 0; r < 16; ++r) p0[r] = __builtin_amdgcn_exp2f(fmaf(p0[r], C2, mnL));
; #pragma unroll
;     for (int r = 0; r < 16; ++r) p1[r] = __builtin_amdgcn_exp2f(fmaf(p1[r], C2, mnL));
; }
; __device__ __forceinline__ void finishSM(const f32x16& p0, const f32x16& p1, float alpha, float& l_reg, half8& pa0, half8& pa1, half8& pa2, half8& pa3) {
;     f32x2 s2 = {0.f, 0.f};
; #pragma unroll
;     for (int r = 0; r < 16; r += 2) { s2 += (f32x2){p0[r], p0[r + 1]}; s2 += (f32x2){p1[r], p1[r + 1]}; }
;     float ps = s2[0] + s2[1];
;     { auto rr = __builtin_amdgcn_permlane32_swap(__float_as_uint(ps), __float_as_uint(ps), false, false);
;       ps = __uint_as_float(rr[0]) + __uint_as_float(rr[1]); }
;     l_reg = l_reg * alpha + ps;
;     ...
;     FA_PK4(p0, 0, pa0); FA_PK4(p0, 8, pa1); FA_PK4(p1, 0, pa2); FA_PK4(p1, 8, pa3);
; __device__ __forceinline__ void pv_tile2(f32x16* o, int vb0, half8 pa0, half8 pa1, half8 pa2, half8 pa3) {
;     ...
;     s16x4 al0, al1, al2, al3, ah0, ah1, ah2, ah3, bl0, bl1, bl2, bl3, bh0, bh1, bh2, bh3;
;     FA_RD8(a, 0);
;     FA_RD8(b, 1); asm volatile("s_waitcnt lgkmcnt(8)" ::: "memory"); FA_SBAR(); FA_MM4(a, 0); FA_SBAR();
;     FA_RD8(a, 2); asm volatile("s_waitcnt lgkmcnt(8)" ::: "memory"); FA_SBAR(); FA_MM4(b, 1); FA_SBAR();
;     FA_RD8(b, 3); asm volatile("s_waitcnt lgkmcnt(8)" ::: "memory"); FA_SBAR(); FA_MM4(a, 2); FA_SBAR();
;     asm volatile("s_waitcnt lgkmcnt(0)" ::: "memory"); FA_SBAR(); FA_MM4(b, 3);
.Ldsa_fast:
.LBB0_4939:
	v_mul_f32_e32 v193, 0xbe0293ee, v186
	v_fmamk_f32 v6, v6, 0x3e0293ee, v193
	v_exp_f32_e32 v104, v6
	v_fmamk_f32 v6, v7, 0x3e0293ee, v193
	v_exp_f32_e32 v105, v6
	v_fmamk_f32 v6, v8, 0x3e0293ee, v193
	v_exp_f32_e32 v106, v6
	v_fmamk_f32 v6, v9, 0x3e0293ee, v193
	v_exp_f32_e32 v107, v6
	v_fmamk_f32 v6, v10, 0x3e0293ee, v193
	v_exp_f32_e32 v108, v6
	v_fmamk_f32 v6, v11, 0x3e0293ee, v193
	v_exp_f32_e32 v109, v6
	v_fmamk_f32 v6, v12, 0x3e0293ee, v193
	v_exp_f32_e32 v110, v6
	v_fmamk_f32 v6, v13, 0x3e0293ee, v193
	v_exp_f32_e32 v111, v6
	v_fmamk_f32 v6, v14, 0x3e0293ee, v193
	v_exp_f32_e32 v112, v6
	v_fmamk_f32 v6, v15, 0x3e0293ee, v193
	v_fmamk_f32 v102, v188, 0x3e0293ee, v193
	v_fmamk_f32 v98, v98, 0x3e0293ee, v193
	v_exp_f32_e32 v113, v6
	v_fmamk_f32 v6, v16, 0x3e0293ee, v193
	v_exp_f32_e32 v102, v102
	v_exp_f32_e32 v103, v98
	v_exp_f32_e32 v188, v6
	v_fmamk_f32 v6, v17, 0x3e0293ee, v193
	v_fmamk_f32 v98, v99, 0x3e0293ee, v193
	v_fmamk_f32 v99, v100, 0x3e0293ee, v193
	v_exp_f32_e32 v189, v6
	v_fmamk_f32 v6, v82, 0x3e0293ee, v193
	v_exp_f32_e32 v98, v98
	v_exp_f32_e32 v99, v99
	v_exp_f32_e32 v190, v6
	v_fmamk_f32 v6, v83, 0x3e0293ee, v193
	v_fmamk_f32 v100, v101, 0x3e0293ee, v193
	v_fmamk_f32 v87, v87, 0x3e0293ee, v193
	v_exp_f32_e32 v191, v6
	v_fmamk_f32 v6, v84, 0x3e0293ee, v193
	v_exp_f32_e32 v100, v100
	v_exp_f32_e32 v101, v87
	v_fmamk_f32 v87, v88, 0x3e0293ee, v193
	v_exp_f32_e32 v192, v6
	v_pk_add_f32 v[6:7], v[102:103], 0 op_sel_hi:[1,0]
	v_exp_f32_e32 v88, v87
	v_fmamk_f32 v87, v89, 0x3e0293ee, v193
	v_pk_add_f32 v[6:7], v[6:7], v[104:105]
	v_exp_f32_e32 v89, v87
	v_fmamk_f32 v87, v90, 0x3e0293ee, v193
	v_pk_add_f32 v[6:7], v[6:7], v[98:99]
	v_exp_f32_e32 v90, v87
	v_fmamk_f32 v87, v91, 0x3e0293ee, v193
	v_pk_add_f32 v[6:7], v[6:7], v[106:107]
	v_exp_f32_e32 v91, v87
	v_fmamk_f32 v87, v92, 0x3e0293ee, v193
	v_pk_add_f32 v[6:7], v[6:7], v[100:101]
	v_exp_f32_e32 v92, v87
	v_fmamk_f32 v87, v93, 0x3e0293ee, v193
	v_pk_add_f32 v[6:7], v[6:7], v[108:109]
	v_exp_f32_e32 v93, v87
	v_fmamk_f32 v87, v94, 0x3e0293ee, v193
	v_pk_add_f32 v[6:7], v[6:7], v[88:89]
	v_exp_f32_e32 v94, v87
	v_fmamk_f32 v87, v95, 0x3e0293ee, v193
	v_pk_add_f32 v[6:7], v[6:7], v[110:111]
	v_exp_f32_e32 v95, v87
	v_fmamk_f32 v87, v96, 0x3e0293ee, v193
	v_pk_add_f32 v[6:7], v[6:7], v[90:91]
	v_exp_f32_e32 v96, v87
	v_fmamk_f32 v87, v97, 0x3e0293ee, v193
	v_pk_add_f32 v[6:7], v[6:7], v[112:113]
	v_exp_f32_e32 v97, v87
	v_fmac_f32_e32 v193, 0x3e0293ee, v85
	v_pk_add_f32 v[6:7], v[6:7], v[92:93]
	v_exp_f32_e32 v193, v193
	v_pk_add_f32 v[6:7], v[6:7], v[188:189]
	v_cvt_pk_f16_f32 v8, v100, v101
	v_pk_add_f32 v[6:7], v[94:95], v[6:7]
	v_cvt_pk_f16_f32 v9, v88, v89
	v_pk_add_f32 v[6:7], v[190:191], v[6:7]
	v_cvt_pk_f16_f32 v10, v90, v91
	v_pk_add_f32 v[6:7], v[96:97], v[6:7]
	v_cvt_pk_f16_f32 v11, v92, v93
	v_pk_add_f32 v[6:7], v[192:193], v[6:7]
	v_cvt_pk_f16_f32 v12, v94, v95
	v_pk_add_f32 v[6:7], v[6:7], v[6:7] op_sel:[0,1] op_sel_hi:[1,0]
	v_cvt_pk_f16_f32 v13, v96, v97
	v_mov_b32_e32 v7, v6
	s_nop 1
	v_permlane32_swap_b32_e32 v6, v7
	v_add_f32_e32 v194, v6, v7
	v_cvt_pk_f16_f32 v6, v102, v103
	v_cvt_pk_f16_f32 v7, v98, v99
	v_cvt_pk_f16_f32 v14, v104, v105
	v_cvt_pk_f16_f32 v15, v106, v107
	v_cvt_pk_f16_f32 v16, v108, v109
	v_cvt_pk_f16_f32 v17, v110, v111
	v_cvt_pk_f16_f32 v82, v112, v113
	v_cvt_pk_f16_f32 v83, v188, v189
	v_cvt_pk_f16_f32 v84, v190, v191
	v_cvt_pk_f16_f32 v85, v192, v193
	v_fmac_f32_e32 v194, v187, v86
	v_permlane32_swap_b32_e32 v6, v8
	v_permlane32_swap_b32_e32 v7, v9
	v_permlane32_swap_b32_e32 v10, v12
	v_permlane32_swap_b32_e32 v11, v13
	v_permlane32_swap_b32_e32 v14, v16
	v_permlane32_swap_b32_e32 v15, v17
	v_permlane32_swap_b32_e32 v82, v84
	v_permlane32_swap_b32_e32 v83, v85
	v_add_u32_e32 v2, v185, v2
	ds_read_b64_tr_b16 v[86:87], v2 offset:0
	ds_read_b64_tr_b16 v[88:89], v2 offset:0x800
	ds_read_b64_tr_b16 v[90:91], v2 offset:0x1000
	ds_read_b64_tr_b16 v[92:93], v2 offset:0x1800
	ds_read_b64_tr_b16 v[94:95], v2 offset:0x2000
	ds_read_b64_tr_b16 v[96:97], v2 offset:0x2800
	ds_read_b64_tr_b16 v[98:99], v2 offset:0x3000
	ds_read_b64_tr_b16 v[100:101], v2 offset:0x3800
	ds_read_b64_tr_b16 v[102:103], v2 offset:0x200
	ds_read_b64_tr_b16 v[104:105], v2 offset:0xa00
	ds_read_b64_tr_b16 v[106:107], v2 offset:0x1200
	ds_read_b64_tr_b16 v[108:109], v2 offset:0x1a00
	ds_read_b64_tr_b16 v[110:111], v2 offset:0x2200
	ds_read_b64_tr_b16 v[112:113], v2 offset:0x2a00
	ds_read_b64_tr_b16 v[188:189], v2 offset:0x3200
	ds_read_b64_tr_b16 v[190:191], v2 offset:0x3a00
	s_waitcnt lgkmcnt(14)
	s_nop 0
	v_mfma_f32_32x32x16_f16 v[66:81], v[6:9], v[86:89], v[66:81]
	s_waitcnt lgkmcnt(12)
	v_mfma_f32_32x32x16_f16 v[66:81], v[10:13], v[90:93], v[66:81]
	s_waitcnt lgkmcnt(10)
	v_mfma_f32_32x32x16_f16 v[66:81], v[14:17], v[94:97], v[66:81]
	s_waitcnt lgkmcnt(8)
	v_mfma_f32_32x32x16_f16 v[66:81], v[82:85], v[98:101], v[66:81]
	ds_read_b64_tr_b16 v[86:87], v2 offset:0x400
	ds_read_b64_tr_b16 v[88:89], v2 offset:0xc00
	ds_read_b64_tr_b16 v[90:91], v2 offset:0x1400
	ds_read_b64_tr_b16 v[92:93], v2 offset:0x1c00
	ds_read_b64_tr_b16 v[94:95], v2 offset:0x2400
	ds_read_b64_tr_b16 v[96:97], v2 offset:0x2c00
	ds_read_b64_tr_b16 v[98:99], v2 offset:0x3400
	ds_read_b64_tr_b16 v[100:101], v2 offset:0x3c00
	s_waitcnt lgkmcnt(8)
	v_mfma_f32_32x32x16_f16 v[50:65], v[6:9], v[102:105], v[50:65]
	v_mfma_f32_32x32x16_f16 v[50:65], v[10:13], v[106:109], v[50:65]
	v_mfma_f32_32x32x16_f16 v[50:65], v[14:17], v[110:113], v[50:65]
	v_mfma_f32_32x32x16_f16 v[50:65], v[82:85], v[188:191], v[50:65]
	ds_read_b64_tr_b16 v[102:103], v2 offset:0x600
	ds_read_b64_tr_b16 v[104:105], v2 offset:0xe00
	ds_read_b64_tr_b16 v[106:107], v2 offset:0x1600
	ds_read_b64_tr_b16 v[108:109], v2 offset:0x1e00
	ds_read_b64_tr_b16 v[110:111], v2 offset:0x2600
	ds_read_b64_tr_b16 v[112:113], v2 offset:0x2e00
	ds_read_b64_tr_b16 v[188:189], v2 offset:0x3600
	ds_read_b64_tr_b16 v[190:191], v2 offset:0x3e00
	s_waitcnt lgkmcnt(8)
	v_mfma_f32_32x32x16_f16 v[34:49], v[6:9], v[86:89], v[34:49]
	v_mfma_f32_32x32x16_f16 v[34:49], v[10:13], v[90:93], v[34:49]
	v_mfma_f32_32x32x16_f16 v[34:49], v[14:17], v[94:97], v[34:49]
	v_mfma_f32_32x32x16_f16 v[34:49], v[82:85], v[98:101], v[34:49]
	s_waitcnt lgkmcnt(0)
	v_mfma_f32_32x32x16_f16 v[18:33], v[6:9], v[102:105], v[18:33]
	v_mov_b32_e32 v187, v194
	v_mfma_f32_32x32x16_f16 v[18:33], v[10:13], v[106:109], v[18:33]
	v_mfma_f32_32x32x16_f16 v[18:33], v[14:17], v[110:113], v[18:33]
	v_mfma_f32_32x32x16_f16 v[18:33], v[82:85], v[188:191], v[18:33]

; #define FA_SBAR() __builtin_amdgcn_sched_barrier(0)
; #define FA_RD8(S, d0) do { constexpr int b_ = v_rd_off(d0, 0, 0); FA_TRRD(S##l0, b_); FA_TRRD(S##h0, b_ + 2048); FA_TRRD(S##l1, b_ + 4096); FA_TRRD(S##h1, b_ + 6144); FA_TRRD(S##l2, b_ + 8192); FA_TRRD(S##h2, b_ + 10240); FA_TRRD(S##l3, b_ + 12288); FA_TRRD(S##h3, b_ + 14336); } while (0)
; __device__ __forceinline__ void partialSM(f32x16& p0, f32x16& p1, float& m_reg, float& mn, float& alpha, const float sc, const float C2) {
;     ...
;     const float mnL = -mn * C2;
; #pragma unroll
;     for (int r = 0; r < 16; ++r) p0[r] = __builtin_amdgcn_exp2f(fmaf(p0[r], C2, mnL));
; #pragma unroll
;     for (int r = 0; r < 16; ++r) p1[r] = __builtin_amdgcn_exp2f(fmaf(p1[r], C2, mnL));
; }
; __device__ __forceinline__ void finishSM(const f32x16& p0, const f32x16& p1, float alpha, float& l_reg, half8& pa0, half8& pa1, half8& pa2, half8& pa3) {
;     f32x2 s2 = {0.f, 0.f};
; #pragma unroll
;     for (int r = 0; r < 16; r += 2) { s2 += (f32x2){p0[r], p0[r + 1]}; s2 += (f32x2){p1[r], p1[r + 1]}; }
;     float ps = s2[0] + s2[1];
;     { auto rr = __builtin_amdgcn_permlane32_swap(__float_as_uint(ps), __float_as_uint(ps), false, false);
;       ps = __uint_as_float(rr[0]) + __uint_as_float(rr[1]); }
;     l_reg = l_reg * alpha + ps;
;     ...
;     FA_PK4(p0, 0, pa0); FA_PK4(p0, 8, pa1); FA_PK4(p1, 0, pa2); FA_PK4(p1, 8, pa3);
; __device__ __forceinline__ void pv_tile2(f32x16* o, int vb0, half8 pa0, half8 pa1, half8 pa2, half8 pa3) {
;     ...
;     s16x4 al0, al1, al2, al3, ah0, ah1, ah2, ah3, bl0, bl1, bl2, bl3, bh0, bh1, bh2, bh3;
;     FA_RD8(a, 0);
;     FA_RD8(b, 1); asm volatile("s_waitcnt lgkmcnt(8)" ::: "memory"); FA_SBAR(); FA_MM4(a, 0); FA_SBAR();
;     FA_RD8(a, 2); asm volatile("s_waitcnt lgkmcnt(8)" ::: "memory"); FA_SBAR(); FA_MM4(b, 1); FA_SBAR();
;     FA_RD8(b, 3); asm volatile("s_waitcnt lgkmcnt(8)" ::: "memory"); FA_SBAR(); FA_MM4(a, 2); FA_SBAR();
;     asm volatile("s_waitcnt lgkmcnt(0)" ::: "memory"); FA_SBAR(); FA_MM4(b, 3);
.Lmoba_fast:
.LBB0_4961:
	v_mul_f32_e32 v5, 0xbe0293ee, v236
	v_fmamk_f32 v6, v98, 0x3e0293ee, v5
	v_fmamk_f32 v7, v99, 0x3e0293ee, v5
	v_exp_f32_e32 v6, v6
	v_exp_f32_e32 v7, v7
	v_fmamk_f32 v82, v82, 0x3e0293ee, v5
	v_fmamk_f32 v83, v83, 0x3e0293ee, v5
	v_fmamk_f32 v8, v100, 0x3e0293ee, v5
	v_fmamk_f32 v9, v101, 0x3e0293ee, v5
	v_exp_f32_e32 v82, v82
	v_exp_f32_e32 v83, v83
	v_exp_f32_e32 v8, v8
	v_exp_f32_e32 v9, v9
	v_fmamk_f32 v84, v84, 0x3e0293ee, v5
	v_fmamk_f32 v85, v85, 0x3e0293ee, v5
	v_fmamk_f32 v10, v102, 0x3e0293ee, v5
	v_fmamk_f32 v11, v103, 0x3e0293ee, v5
	v_exp_f32_e32 v84, v84
	v_exp_f32_e32 v85, v85
	v_exp_f32_e32 v10, v10
	v_exp_f32_e32 v11, v11
	v_fmamk_f32 v86, v86, 0x3e0293ee, v5
	v_fmamk_f32 v87, v87, 0x3e0293ee, v5
	v_pk_add_f32 v[102:103], v[6:7], 0 op_sel_hi:[1,0]
	v_fmamk_f32 v12, v104, 0x3e0293ee, v5
	v_fmamk_f32 v13, v105, 0x3e0293ee, v5
	v_exp_f32_e32 v86, v86
	v_exp_f32_e32 v87, v87
	v_pk_add_f32 v[102:103], v[82:83], v[102:103]
	v_exp_f32_e32 v12, v12
	v_exp_f32_e32 v13, v13
	v_fmamk_f32 v88, v88, 0x3e0293ee, v5
	v_fmamk_f32 v89, v89, 0x3e0293ee, v5
	v_pk_add_f32 v[102:103], v[8:9], v[102:103]
	v_fmamk_f32 v14, v106, 0x3e0293ee, v5
	v_fmamk_f32 v15, v107, 0x3e0293ee, v5
	v_exp_f32_e32 v88, v88
	v_exp_f32_e32 v89, v89
	v_pk_add_f32 v[102:103], v[84:85], v[102:103]
	v_exp_f32_e32 v14, v14
	v_exp_f32_e32 v15, v15
	v_fmamk_f32 v90, v90, 0x3e0293ee, v5
	v_fmamk_f32 v91, v91, 0x3e0293ee, v5
	v_pk_add_f32 v[102:103], v[10:11], v[102:103]
	v_fmamk_f32 v16, v108, 0x3e0293ee, v5
	v_fmamk_f32 v17, v109, 0x3e0293ee, v5
	v_exp_f32_e32 v90, v90
	v_exp_f32_e32 v91, v91
	v_pk_add_f32 v[102:103], v[86:87], v[102:103]
	v_exp_f32_e32 v16, v16
	v_exp_f32_e32 v17, v17
	v_fmamk_f32 v92, v92, 0x3e0293ee, v5
	v_fmamk_f32 v93, v93, 0x3e0293ee, v5
	v_pk_add_f32 v[102:103], v[12:13], v[102:103]
	v_fmamk_f32 v98, v110, 0x3e0293ee, v5
	v_fmamk_f32 v99, v111, 0x3e0293ee, v5
	v_exp_f32_e32 v92, v92
	v_exp_f32_e32 v93, v93
	v_pk_add_f32 v[102:103], v[88:89], v[102:103]
	v_exp_f32_e32 v98, v98
	v_exp_f32_e32 v99, v99
	v_fmamk_f32 v94, v94, 0x3e0293ee, v5
	v_fmamk_f32 v95, v95, 0x3e0293ee, v5
	v_pk_add_f32 v[102:103], v[14:15], v[102:103]
	v_fmamk_f32 v100, v112, 0x3e0293ee, v5
	v_fmamk_f32 v101, v113, 0x3e0293ee, v5
	v_exp_f32_e32 v94, v94
	v_exp_f32_e32 v95, v95
	v_pk_add_f32 v[102:103], v[90:91], v[102:103]
	v_exp_f32_e32 v100, v100
	v_exp_f32_e32 v101, v101
	v_fmamk_f32 v96, v96, 0x3e0293ee, v5
	v_fmac_f32_e32 v5, 0x3e0293ee, v97
	v_pk_add_f32 v[102:103], v[16:17], v[102:103]
	v_exp_f32_e32 v96, v96
	v_exp_f32_e32 v97, v5
	v_pk_add_f32 v[102:103], v[92:93], v[102:103]
	v_cvt_pk_f16_f32 v4, v6, v7
	v_pk_add_f32 v[102:103], v[98:99], v[102:103]
	v_cvt_pk_f16_f32 v5, v8, v9
	v_pk_add_f32 v[102:103], v[94:95], v[102:103]
	v_cvt_pk_f16_f32 v6, v10, v11
	v_pk_add_f32 v[102:103], v[100:101], v[102:103]
	v_cvt_pk_f16_f32 v7, v12, v13
	v_pk_add_f32 v[102:103], v[96:97], v[102:103]
	v_cvt_pk_f16_f32 v8, v14, v15
	v_pk_add_f32 v[102:103], v[102:103], v[102:103] op_sel:[0,1] op_sel_hi:[1,0]
	v_cvt_pk_f16_f32 v9, v16, v17
	v_mov_b32_e32 v103, v102
	v_cvt_pk_f16_f32 v10, v98, v99
	v_cvt_pk_f16_f32 v11, v100, v101
	v_permlane32_swap_b32_e32 v102, v103
	v_cvt_pk_f16_f32 v12, v82, v83
	v_add_f32_e32 v103, v102, v103
	v_cvt_pk_f16_f32 v13, v84, v85
	v_fma_f32 v237, v237, v118, v103
	v_cvt_pk_f16_f32 v14, v86, v87
	v_cvt_pk_f16_f32 v15, v88, v89
	v_cvt_pk_f16_f32 v82, v90, v91
	v_cvt_pk_f16_f32 v83, v92, v93
	v_cvt_pk_f16_f32 v84, v94, v95
	v_cvt_pk_f16_f32 v85, v96, v97
	v_permlane32_swap_b32_e32 v4, v6
	v_permlane32_swap_b32_e32 v5, v7
	v_permlane32_swap_b32_e32 v8, v10
	v_permlane32_swap_b32_e32 v9, v11
	v_permlane32_swap_b32_e32 v12, v14
	v_permlane32_swap_b32_e32 v13, v15
	v_permlane32_swap_b32_e32 v82, v84
	v_permlane32_swap_b32_e32 v83, v85
	v_add_u32_e32 v2, v234, v2
	ds_read_b64_tr_b16 v[86:87], v2 offset:0
	ds_read_b64_tr_b16 v[88:89], v2 offset:0x800
	ds_read_b64_tr_b16 v[90:91], v2 offset:0x1000
	ds_read_b64_tr_b16 v[92:93], v2 offset:0x1800
	ds_read_b64_tr_b16 v[94:95], v2 offset:0x2000
	ds_read_b64_tr_b16 v[96:97], v2 offset:0x2800
	ds_read_b64_tr_b16 v[98:99], v2 offset:0x3000
	ds_read_b64_tr_b16 v[100:101], v2 offset:0x3800
	ds_read_b64_tr_b16 v[102:103], v2 offset:0x200
	ds_read_b64_tr_b16 v[104:105], v2 offset:0xa00
	ds_read_b64_tr_b16 v[106:107], v2 offset:0x1200
	ds_read_b64_tr_b16 v[108:109], v2 offset:0x1a00
	ds_read_b64_tr_b16 v[110:111], v2 offset:0x2200
	ds_read_b64_tr_b16 v[112:113], v2 offset:0x2a00
	ds_read_b64_tr_b16 v[114:115], v2 offset:0x3200
	ds_read_b64_tr_b16 v[116:117], v2 offset:0x3a00
	s_waitcnt lgkmcnt(14)
	s_nop 0
	v_mfma_f32_32x32x16_f16 v[66:81], v[4:7], v[86:89], v[66:81]
	s_waitcnt lgkmcnt(12)
	v_mfma_f32_32x32x16_f16 v[66:81], v[8:11], v[90:93], v[66:81]
	s_waitcnt lgkmcnt(10)
	v_mfma_f32_32x32x16_f16 v[66:81], v[12:15], v[94:97], v[66:81]
	s_waitcnt lgkmcnt(8)
	v_mfma_f32_32x32x16_f16 v[66:81], v[82:85], v[98:101], v[66:81]
	ds_read_b64_tr_b16 v[86:87], v2 offset:0x400
	ds_read_b64_tr_b16 v[88:89], v2 offset:0xc00
	ds_read_b64_tr_b16 v[90:91], v2 offset:0x1400
	ds_read_b64_tr_b16 v[92:93], v2 offset:0x1c00
	ds_read_b64_tr_b16 v[94:95], v2 offset:0x2400
	ds_read_b64_tr_b16 v[96:97], v2 offset:0x2c00
	ds_read_b64_tr_b16 v[98:99], v2 offset:0x3400
	ds_read_b64_tr_b16 v[100:101], v2 offset:0x3c00
	s_waitcnt lgkmcnt(8)
	v_mfma_f32_32x32x16_f16 v[50:65], v[4:7], v[102:105], v[50:65]
	v_mfma_f32_32x32x16_f16 v[50:65], v[8:11], v[106:109], v[50:65]
	v_mfma_f32_32x32x16_f16 v[50:65], v[12:15], v[110:113], v[50:65]
	v_mfma_f32_32x32x16_f16 v[50:65], v[82:85], v[114:117], v[50:65]
	ds_read_b64_tr_b16 v[102:103], v2 offset:0x600
	ds_read_b64_tr_b16 v[104:105], v2 offset:0xe00
	ds_read_b64_tr_b16 v[106:107], v2 offset:0x1600
	ds_read_b64_tr_b16 v[108:109], v2 offset:0x1e00
	ds_read_b64_tr_b16 v[110:111], v2 offset:0x2600
	ds_read_b64_tr_b16 v[112:113], v2 offset:0x2e00
	ds_read_b64_tr_b16 v[114:115], v2 offset:0x3600
	ds_read_b64_tr_b16 v[116:117], v2 offset:0x3e00
	s_waitcnt lgkmcnt(8)
	v_mfma_f32_32x32x16_f16 v[34:49], v[4:7], v[86:89], v[34:49]
	v_mfma_f32_32x32x16_f16 v[34:49], v[8:11], v[90:93], v[34:49]
	v_mfma_f32_32x32x16_f16 v[34:49], v[12:15], v[94:97], v[34:49]
	v_mfma_f32_32x32x16_f16 v[34:49], v[82:85], v[98:101], v[34:49]
	s_waitcnt lgkmcnt(0)
	v_mfma_f32_32x32x16_f16 v[18:33], v[4:7], v[102:105], v[18:33]
	v_mfma_f32_32x32x16_f16 v[18:33], v[8:11], v[106:109], v[18:33]
	v_mfma_f32_32x32x16_f16 v[18:33], v[12:15], v[110:113], v[18:33]
	v_mfma_f32_32x32x16_f16 v[18:33], v[82:85], v[114:117], v[18:33]

; #define FA_SBAR() __builtin_amdgcn_sched_barrier(0)
; #define FA_RD8(S, d0) do { constexpr int b_ = v_rd_off(d0, 0, 0); FA_TRRD(S##l0, b_); FA_TRRD(S##h0, b_ + 2048); FA_TRRD(S##l1, b_ + 4096); FA_TRRD(S##h1, b_ + 6144); FA_TRRD(S##l2, b_ + 8192); FA_TRRD(S##h2, b_ + 10240); FA_TRRD(S##l3, b_ + 12288); FA_TRRD(S##h3, b_ + 14336); } while (0)
; __device__ __forceinline__ void partialSM(f32x16& p0, f32x16& p1, float& m_reg, float& mn, float& alpha, const float sc, const float C2) {
;     ...
;     const float mnL = -mn * C2;
; #pragma unroll
;     for (int r = 0; r < 16; ++r) p0[r] = __builtin_amdgcn_exp2f(fmaf(p0[r], C2, mnL));
; #pragma unroll
;     for (int r = 0; r < 16; ++r) p1[r] = __builtin_amdgcn_exp2f(fmaf(p1[r], C2, mnL));
; }
; __device__ __forceinline__ void finishSM(const f32x16& p0, const f32x16& p1, float alpha, float& l_reg, half8& pa0, half8& pa1, half8& pa2, half8& pa3) {
;     f32x2 s2 = {0.f, 0.f};
; #pragma unroll
;     for (int r = 0; r < 16; r += 2) { s2 += (f32x2){p0[r], p0[r + 1]}; s2 += (f32x2){p1[r], p1[r + 1]}; }
;     float ps = s2[0] + s2[1];
;     { auto rr = __builtin_amdgcn_permlane32_swap(__float_as_uint(ps), __float_as_uint(ps), false, false);
;       ps = __uint_as_float(rr[0]) + __uint_as_float(rr[1]); }
;     l_reg = l_reg * alpha + ps;
;     ...
;     FA_PK4(p0, 0, pa0); FA_PK4(p0, 8, pa1); FA_PK4(p1, 0, pa2); FA_PK4(p1, 8, pa3);
; __device__ __forceinline__ void pv_tile2(f32x16* o, int vb0, half8 pa0, half8 pa1, half8 pa2, half8 pa3) {
;     ...
;     s16x4 al0, al1, al2, al3, ah0, ah1, ah2, ah3, bl0, bl1, bl2, bl3, bh0, bh1, bh2, bh3;
;     FA_RD8(a, 0);
;     FA_RD8(b, 1); asm volatile("s_waitcnt lgkmcnt(8)" ::: "memory"); FA_SBAR(); FA_MM4(a, 0); FA_SBAR();
;     FA_RD8(a, 2); asm volatile("s_waitcnt lgkmcnt(8)" ::: "memory"); FA_SBAR(); FA_MM4(b, 1); FA_SBAR();
;     FA_RD8(b, 3); asm volatile("s_waitcnt lgkmcnt(8)" ::: "memory"); FA_SBAR(); FA_MM4(a, 2); FA_SBAR();
;     asm volatile("s_waitcnt lgkmcnt(0)" ::: "memory"); FA_SBAR(); FA_MM4(b, 3);
.Lmla_fast:
.LBB0_4981:
	v_mul_f32_e32 v5, 0xbdd53b94, v228
	v_fmamk_f32 v6, v98, 0x3dd53b94, v5
	v_fmamk_f32 v7, v99, 0x3dd53b94, v5
	v_exp_f32_e32 v6, v6
	v_exp_f32_e32 v7, v7
	v_fmamk_f32 v82, v82, 0x3dd53b94, v5
	v_fmamk_f32 v83, v83, 0x3dd53b94, v5
	v_fmamk_f32 v8, v100, 0x3dd53b94, v5
	v_fmamk_f32 v9, v101, 0x3dd53b94, v5
	v_exp_f32_e32 v82, v82
	v_exp_f32_e32 v83, v83
	v_exp_f32_e32 v8, v8
	v_exp_f32_e32 v9, v9
	v_fmamk_f32 v84, v84, 0x3dd53b94, v5
	v_fmamk_f32 v85, v85, 0x3dd53b94, v5
	v_fmamk_f32 v10, v102, 0x3dd53b94, v5
	v_fmamk_f32 v11, v103, 0x3dd53b94, v5
	v_exp_f32_e32 v84, v84
	v_exp_f32_e32 v85, v85
	v_exp_f32_e32 v10, v10
	v_exp_f32_e32 v11, v11
	v_fmamk_f32 v86, v86, 0x3dd53b94, v5
	v_fmamk_f32 v87, v87, 0x3dd53b94, v5
	v_pk_add_f32 v[102:103], v[6:7], 0 op_sel_hi:[1,0]
	v_fmamk_f32 v12, v104, 0x3dd53b94, v5
	v_fmamk_f32 v13, v105, 0x3dd53b94, v5
	v_exp_f32_e32 v86, v86
	v_exp_f32_e32 v87, v87
	v_pk_add_f32 v[102:103], v[82:83], v[102:103]
	v_exp_f32_e32 v12, v12
	v_exp_f32_e32 v13, v13
	v_fmamk_f32 v88, v88, 0x3dd53b94, v5
	v_fmamk_f32 v89, v89, 0x3dd53b94, v5
	v_pk_add_f32 v[102:103], v[8:9], v[102:103]
	v_fmamk_f32 v14, v106, 0x3dd53b94, v5
	v_fmamk_f32 v15, v107, 0x3dd53b94, v5
	v_exp_f32_e32 v88, v88
	v_exp_f32_e32 v89, v89
	v_pk_add_f32 v[102:103], v[84:85], v[102:103]
	v_exp_f32_e32 v14, v14
	v_exp_f32_e32 v15, v15
	v_fmamk_f32 v90, v90, 0x3dd53b94, v5
	v_fmamk_f32 v91, v91, 0x3dd53b94, v5
	v_pk_add_f32 v[102:103], v[10:11], v[102:103]
	v_fmamk_f32 v16, v108, 0x3dd53b94, v5
	v_fmamk_f32 v17, v109, 0x3dd53b94, v5
	v_exp_f32_e32 v90, v90
	v_exp_f32_e32 v91, v91
	v_pk_add_f32 v[102:103], v[86:87], v[102:103]
	v_exp_f32_e32 v16, v16
	v_exp_f32_e32 v17, v17
	v_fmamk_f32 v92, v92, 0x3dd53b94, v5
	v_fmamk_f32 v93, v93, 0x3dd53b94, v5
	v_pk_add_f32 v[102:103], v[12:13], v[102:103]
	v_fmamk_f32 v98, v110, 0x3dd53b94, v5
	v_fmamk_f32 v99, v111, 0x3dd53b94, v5
	v_exp_f32_e32 v92, v92
	v_exp_f32_e32 v93, v93
	v_pk_add_f32 v[102:103], v[88:89], v[102:103]
	v_exp_f32_e32 v98, v98
	v_exp_f32_e32 v99, v99
	v_fmamk_f32 v94, v94, 0x3dd53b94, v5
	v_fmamk_f32 v95, v95, 0x3dd53b94, v5
	v_pk_add_f32 v[102:103], v[14:15], v[102:103]
	v_fmamk_f32 v100, v112, 0x3dd53b94, v5
	v_fmamk_f32 v101, v113, 0x3dd53b94, v5
	v_exp_f32_e32 v94, v94
	v_exp_f32_e32 v95, v95
	v_pk_add_f32 v[102:103], v[90:91], v[102:103]
	v_exp_f32_e32 v100, v100
	v_exp_f32_e32 v101, v101
	v_fmamk_f32 v96, v96, 0x3dd53b94, v5
	v_fmac_f32_e32 v5, 0x3dd53b94, v97
	v_pk_add_f32 v[102:103], v[16:17], v[102:103]
	v_exp_f32_e32 v96, v96
	v_exp_f32_e32 v97, v5
	v_pk_add_f32 v[102:103], v[92:93], v[102:103]
	v_cvt_pk_f16_f32 v4, v6, v7
	v_pk_add_f32 v[102:103], v[98:99], v[102:103]
	v_cvt_pk_f16_f32 v5, v8, v9
	v_pk_add_f32 v[102:103], v[94:95], v[102:103]
	v_cvt_pk_f16_f32 v6, v10, v11
	v_pk_add_f32 v[102:103], v[100:101], v[102:103]
	v_cvt_pk_f16_f32 v7, v12, v13
	v_pk_add_f32 v[102:103], v[96:97], v[102:103]
	v_cvt_pk_f16_f32 v8, v14, v15
	v_pk_add_f32 v[102:103], v[102:103], v[102:103] op_sel:[0,1] op_sel_hi:[1,0]
	v_cvt_pk_f16_f32 v9, v16, v17
	v_mov_b32_e32 v103, v102
	v_cvt_pk_f16_f32 v10, v98, v99
	v_cvt_pk_f16_f32 v11, v100, v101
	v_permlane32_swap_b32_e32 v102, v103
	v_cvt_pk_f16_f32 v12, v82, v83
	v_add_f32_e32 v103, v102, v103
	v_cvt_pk_f16_f32 v13, v84, v85
	v_fma_f32 v229, v229, v214, v103
	v_cvt_pk_f16_f32 v14, v86, v87
	v_cvt_pk_f16_f32 v15, v88, v89
	v_cvt_pk_f16_f32 v82, v90, v91
	v_cvt_pk_f16_f32 v83, v92, v93
	v_cvt_pk_f16_f32 v84, v94, v95
	v_cvt_pk_f16_f32 v85, v96, v97
	v_permlane32_swap_b32_e32 v4, v6
	v_permlane32_swap_b32_e32 v5, v7
	v_permlane32_swap_b32_e32 v8, v10
	v_permlane32_swap_b32_e32 v9, v11
	v_permlane32_swap_b32_e32 v12, v14
	v_permlane32_swap_b32_e32 v13, v15
	v_permlane32_swap_b32_e32 v82, v84
	v_permlane32_swap_b32_e32 v83, v85
	v_add_u32_e32 v2, v225, v2
	ds_read_b64_tr_b16 v[86:87], v2 offset:0
	ds_read_b64_tr_b16 v[88:89], v2 offset:0x800
	ds_read_b64_tr_b16 v[90:91], v2 offset:0x1000
	ds_read_b64_tr_b16 v[92:93], v2 offset:0x1800
	ds_read_b64_tr_b16 v[94:95], v2 offset:0x2000
	ds_read_b64_tr_b16 v[96:97], v2 offset:0x2800
	ds_read_b64_tr_b16 v[98:99], v2 offset:0x3000
	ds_read_b64_tr_b16 v[100:101], v2 offset:0x3800
	ds_read_b64_tr_b16 v[102:103], v2 offset:0x200
	ds_read_b64_tr_b16 v[104:105], v2 offset:0xa00
	ds_read_b64_tr_b16 v[106:107], v2 offset:0x1200
	ds_read_b64_tr_b16 v[108:109], v2 offset:0x1a00
	ds_read_b64_tr_b16 v[110:111], v2 offset:0x2200
	ds_read_b64_tr_b16 v[112:113], v2 offset:0x2a00
	ds_read_b64_tr_b16 v[194:195], v2 offset:0x3200
	ds_read_b64_tr_b16 v[196:197], v2 offset:0x3a00
	s_waitcnt lgkmcnt(14)
	s_nop 0
	v_mfma_f32_32x32x16_f16 v[66:81], v[4:7], v[86:89], v[66:81]
	s_waitcnt lgkmcnt(12)
	v_mfma_f32_32x32x16_f16 v[66:81], v[8:11], v[90:93], v[66:81]
	s_waitcnt lgkmcnt(10)
	v_mfma_f32_32x32x16_f16 v[66:81], v[12:15], v[94:97], v[66:81]
	s_waitcnt lgkmcnt(8)
	v_mfma_f32_32x32x16_f16 v[66:81], v[82:85], v[98:101], v[66:81]
	ds_read_b64_tr_b16 v[86:87], v2 offset:0x400
	ds_read_b64_tr_b16 v[88:89], v2 offset:0xc00
	ds_read_b64_tr_b16 v[90:91], v2 offset:0x1400
	ds_read_b64_tr_b16 v[92:93], v2 offset:0x1c00
	ds_read_b64_tr_b16 v[94:95], v2 offset:0x2400
	ds_read_b64_tr_b16 v[96:97], v2 offset:0x2c00
	ds_read_b64_tr_b16 v[98:99], v2 offset:0x3400
	ds_read_b64_tr_b16 v[100:101], v2 offset:0x3c00
	s_waitcnt lgkmcnt(8)
	v_mfma_f32_32x32x16_f16 v[50:65], v[4:7], v[102:105], v[50:65]
	v_mfma_f32_32x32x16_f16 v[50:65], v[8:11], v[106:109], v[50:65]
	v_mfma_f32_32x32x16_f16 v[50:65], v[12:15], v[110:113], v[50:65]
	v_mfma_f32_32x32x16_f16 v[50:65], v[82:85], v[194:197], v[50:65]
	ds_read_b64_tr_b16 v[102:103], v2 offset:0x600
	ds_read_b64_tr_b16 v[104:105], v2 offset:0xe00
	ds_read_b64_tr_b16 v[106:107], v2 offset:0x1600
	ds_read_b64_tr_b16 v[108:109], v2 offset:0x1e00
	ds_read_b64_tr_b16 v[110:111], v2 offset:0x2600
	ds_read_b64_tr_b16 v[112:113], v2 offset:0x2e00
	ds_read_b64_tr_b16 v[194:195], v2 offset:0x3600
	ds_read_b64_tr_b16 v[196:197], v2 offset:0x3e00
	s_waitcnt lgkmcnt(8)
	v_mfma_f32_32x32x16_f16 v[34:49], v[4:7], v[86:89], v[34:49]
	v_mfma_f32_32x32x16_f16 v[34:49], v[8:11], v[90:93], v[34:49]
	v_mfma_f32_32x32x16_f16 v[34:49], v[12:15], v[94:97], v[34:49]
	v_mfma_f32_32x32x16_f16 v[34:49], v[82:85], v[98:101], v[34:49]
	s_waitcnt lgkmcnt(0)
	v_mfma_f32_32x32x16_f16 v[18:33], v[4:7], v[102:105], v[18:33]
	v_mfma_f32_32x32x16_f16 v[18:33], v[8:11], v[106:109], v[18:33]
	v_mfma_f32_32x32x16_f16 v[18:33], v[12:15], v[110:113], v[18:33]
	v_mfma_f32_32x32x16_f16 v[18:33], v[82:85], v[194:197], v[18:33]

; #define FA_SBAR() __builtin_amdgcn_sched_barrier(0)
; #define FA_RD8(S, d0) do { constexpr int b_ = v_rd_off(d0, 0, 0); FA_TRRD(S##l0, b_); FA_TRRD(S##h0, b_ + 2048); FA_TRRD(S##l1, b_ + 4096); FA_TRRD(S##h1, b_ + 6144); FA_TRRD(S##l2, b_ + 8192); FA_TRRD(S##h2, b_ + 10240); FA_TRRD(S##l3, b_ + 12288); FA_TRRD(S##h3, b_ + 14336); } while (0)
; __device__ __forceinline__ void partialSM(f32x16& p0, f32x16& p1, float& m_reg, float& mn, float& alpha, const float sc, const float C2) {
;     ...
;     const float mnL = -mn * C2;
; #pragma unroll
;     for (int r = 0; r < 16; ++r) p0[r] = __builtin_amdgcn_exp2f(fmaf(p0[r], C2, mnL));
; #pragma unroll
;     for (int r = 0; r < 16; ++r) p1[r] = __builtin_amdgcn_exp2f(fmaf(p1[r], C2, mnL));
; }
; __device__ __forceinline__ void finishSM(const f32x16& p0, const f32x16& p1, float alpha, float& l_reg, half8& pa0, half8& pa1, half8& pa2, half8& pa3) {
;     f32x2 s2 = {0.f, 0.f};
; #pragma unroll
;     for (int r = 0; r < 16; r += 2) { s2 += (f32x2){p0[r], p0[r + 1]}; s2 += (f32x2){p1[r], p1[r + 1]}; }
;     float ps = s2[0] + s2[1];
;     { auto rr = __builtin_amdgcn_permlane32_swap(__float_as_uint(ps), __float_as_uint(ps), false, false);
;       ps = __uint_as_float(rr[0]) + __uint_as_float(rr[1]); }
;     l_reg = l_reg * alpha + ps;
;     ...
;     FA_PK4(p0, 0, pa0); FA_PK4(p0, 8, pa1); FA_PK4(p1, 0, pa2); FA_PK4(p1, 8, pa3);
; __device__ __forceinline__ void pv_tile2(f32x16* o, int vb0, half8 pa0, half8 pa1, half8 pa2, half8 pa3) {
;     ...
;     s16x4 al0, al1, al2, al3, ah0, ah1, ah2, ah3, bl0, bl1, bl2, bl3, bh0, bh1, bh2, bh3;
;     FA_RD8(a, 0);
;     FA_RD8(b, 1); asm volatile("s_waitcnt lgkmcnt(8)" ::: "memory"); FA_SBAR(); FA_MM4(a, 0); FA_SBAR();
;     FA_RD8(a, 2); asm volatile("s_waitcnt lgkmcnt(8)" ::: "memory"); FA_SBAR(); FA_MM4(b, 1); FA_SBAR();
;     FA_RD8(b, 3); asm volatile("s_waitcnt lgkmcnt(8)" ::: "memory"); FA_SBAR(); FA_MM4(a, 2); FA_SBAR();
;     asm volatile("s_waitcnt lgkmcnt(0)" ::: "memory"); FA_SBAR(); FA_MM4(b, 3);
.Lslc_fast:
.LBB0_4999:
	v_mul_f32_e32 v111, 0xbe0293ee, v189
	v_fmamk_f32 v92, v193, 0x3e0293ee, v111
	v_fmamk_f32 v93, v204, 0x3e0293ee, v111
	v_exp_f32_e32 v92, v92
	v_exp_f32_e32 v93, v93
	v_fmamk_f32 v82, v82, 0x3e0293ee, v111
	v_fmamk_f32 v83, v83, 0x3e0293ee, v111
	v_fmamk_f32 v94, v191, 0x3e0293ee, v111
	v_fmamk_f32 v95, v192, 0x3e0293ee, v111
	v_exp_f32_e32 v82, v82
	v_exp_f32_e32 v83, v83
	v_exp_f32_e32 v94, v94
	v_exp_f32_e32 v95, v95
	v_fmamk_f32 v16, v16, 0x3e0293ee, v111
	v_fmamk_f32 v17, v17, 0x3e0293ee, v111
	v_fmamk_f32 v96, v101, 0x3e0293ee, v111
	v_fmamk_f32 v97, v102, 0x3e0293ee, v111
	v_fmamk_f32 v99, v99, 0x3e0293ee, v111
	v_exp_f32_e32 v16, v16
	v_exp_f32_e32 v17, v17
	v_fmamk_f32 v12, v12, 0x3e0293ee, v111
	v_fmamk_f32 v10, v10, 0x3e0293ee, v111
	v_fmamk_f32 v8, v8, 0x3e0293ee, v111
	v_fmamk_f32 v6, v6, 0x3e0293ee, v111
	v_fmamk_f32 v4, v4, 0x3e0293ee, v111
	v_exp_f32_e32 v96, v96
	v_exp_f32_e32 v97, v97
	v_exp_f32_e32 v102, v99
	v_fmamk_f32 v99, v100, 0x3e0293ee, v111
	v_fmamk_f32 v98, v98, 0x3e0293ee, v111
	v_fmamk_f32 v90, v90, 0x3e0293ee, v111
	v_fmamk_f32 v88, v88, 0x3e0293ee, v111
	v_fmamk_f32 v89, v89, 0x3e0293ee, v111
	v_fmamk_f32 v86, v86, 0x3e0293ee, v111
	v_fmamk_f32 v87, v87, 0x3e0293ee, v111
	v_fmamk_f32 v84, v84, 0x3e0293ee, v111
	v_fmamk_f32 v85, v85, 0x3e0293ee, v111
	v_fmamk_f32 v14, v14, 0x3e0293ee, v111
	v_fmamk_f32 v15, v15, 0x3e0293ee, v111
	v_exp_f32_e32 v100, v12
	v_fmamk_f32 v12, v13, 0x3e0293ee, v111
	v_exp_f32_e32 v104, v10
	v_fmamk_f32 v10, v11, 0x3e0293ee, v111
	v_exp_f32_e32 v106, v8
	v_fmamk_f32 v8, v9, 0x3e0293ee, v111
	v_exp_f32_e32 v108, v6
	v_fmamk_f32 v6, v7, 0x3e0293ee, v111
	v_exp_f32_e32 v110, v4
	v_fmac_f32_e32 v111, 0x3e0293ee, v5
	v_pk_add_f32 v[4:5], v[92:93], 0 op_sel_hi:[1,0]
	v_exp_f32_e32 v14, v14
	v_exp_f32_e32 v15, v15
	v_pk_add_f32 v[4:5], v[82:83], v[4:5]
	v_exp_f32_e32 v103, v99
	v_pk_add_f32 v[4:5], v[94:95], v[4:5]
	v_exp_f32_e32 v101, v12
	v_pk_add_f32 v[4:5], v[16:17], v[4:5]
	v_exp_f32_e32 v98, v98
	v_exp_f32_e32 v99, v90
	v_pk_add_f32 v[4:5], v[96:97], v[4:5]
	v_exp_f32_e32 v105, v10
	v_pk_add_f32 v[4:5], v[14:15], v[4:5]
	v_exp_f32_e32 v88, v88
	v_exp_f32_e32 v89, v89
	v_pk_add_f32 v[4:5], v[102:103], v[4:5]
	v_exp_f32_e32 v107, v8
	v_pk_add_f32 v[4:5], v[100:101], v[4:5]
	v_exp_f32_e32 v86, v86
	v_exp_f32_e32 v87, v87
	v_pk_add_f32 v[4:5], v[98:99], v[4:5]
	v_exp_f32_e32 v109, v6
	v_pk_add_f32 v[4:5], v[104:105], v[4:5]
	v_exp_f32_e32 v84, v84
	v_exp_f32_e32 v85, v85
	v_pk_add_f32 v[4:5], v[88:89], v[4:5]
	v_exp_f32_e32 v111, v111
	v_pk_add_f32 v[4:5], v[106:107], v[4:5]
	v_cvt_pk_f16_f32 v6, v96, v97
	v_pk_add_f32 v[4:5], v[86:87], v[4:5]
	v_cvt_pk_f16_f32 v7, v102, v103
	v_pk_add_f32 v[4:5], v[108:109], v[4:5]
	v_cvt_pk_f16_f32 v8, v98, v99
	v_pk_add_f32 v[4:5], v[84:85], v[4:5]
	v_cvt_pk_f16_f32 v9, v88, v89
	v_pk_add_f32 v[4:5], v[110:111], v[4:5]
	v_cvt_pk_f16_f32 v10, v86, v87
	v_pk_add_f32 v[4:5], v[4:5], v[4:5] op_sel:[0,1] op_sel_hi:[1,0]
	v_cvt_pk_f16_f32 v11, v84, v85
	v_mov_b32_e32 v5, v4
	s_nop 1
	v_permlane32_swap_b32_e32 v4, v5
	v_add_f32_e32 v196, v4, v5
	v_cvt_pk_f16_f32 v4, v92, v93
	v_cvt_pk_f16_f32 v5, v94, v95
	v_cvt_pk_f16_f32 v12, v82, v83
	v_cvt_pk_f16_f32 v13, v16, v17
	v_cvt_pk_f16_f32 v14, v14, v15
	v_cvt_pk_f16_f32 v15, v100, v101
	v_cvt_pk_f16_f32 v82, v104, v105
	v_cvt_pk_f16_f32 v83, v106, v107
	v_cvt_pk_f16_f32 v84, v108, v109
	v_cvt_pk_f16_f32 v85, v110, v111
	v_fmac_f32_e32 v196, v190, v91
	v_permlane32_swap_b32_e32 v4, v6
	v_permlane32_swap_b32_e32 v5, v7
	v_permlane32_swap_b32_e32 v8, v10
	v_permlane32_swap_b32_e32 v9, v11
	v_permlane32_swap_b32_e32 v12, v14
	v_permlane32_swap_b32_e32 v13, v15
	v_permlane32_swap_b32_e32 v82, v84
	v_permlane32_swap_b32_e32 v83, v85
	v_add_u32_e32 v2, v187, v2
	ds_read_b64_tr_b16 v[86:87], v2 offset:0
	ds_read_b64_tr_b16 v[88:89], v2 offset:0x800
	ds_read_b64_tr_b16 v[90:91], v2 offset:0x1000
	ds_read_b64_tr_b16 v[92:93], v2 offset:0x1800
	ds_read_b64_tr_b16 v[94:95], v2 offset:0x2000
	ds_read_b64_tr_b16 v[96:97], v2 offset:0x2800
	ds_read_b64_tr_b16 v[98:99], v2 offset:0x3000
	ds_read_b64_tr_b16 v[100:101], v2 offset:0x3800
	ds_read_b64_tr_b16 v[102:103], v2 offset:0x200
	ds_read_b64_tr_b16 v[104:105], v2 offset:0xa00
	ds_read_b64_tr_b16 v[106:107], v2 offset:0x1200
	ds_read_b64_tr_b16 v[108:109], v2 offset:0x1a00
	ds_read_b64_tr_b16 v[110:111], v2 offset:0x2200
	ds_read_b64_tr_b16 v[112:113], v2 offset:0x2a00
	ds_read_b64_tr_b16 v[190:191], v2 offset:0x3200
	ds_read_b64_tr_b16 v[192:193], v2 offset:0x3a00
	s_waitcnt lgkmcnt(14)
	s_nop 0
	v_mfma_f32_32x32x16_f16 v[66:81], v[4:7], v[86:89], v[66:81]
	s_waitcnt lgkmcnt(12)
	v_mfma_f32_32x32x16_f16 v[66:81], v[8:11], v[90:93], v[66:81]
	s_waitcnt lgkmcnt(10)
	v_mfma_f32_32x32x16_f16 v[66:81], v[12:15], v[94:97], v[66:81]
	s_waitcnt lgkmcnt(8)
	v_mfma_f32_32x32x16_f16 v[66:81], v[82:85], v[98:101], v[66:81]
	ds_read_b64_tr_b16 v[86:87], v2 offset:0x400
	ds_read_b64_tr_b16 v[88:89], v2 offset:0xc00
	ds_read_b64_tr_b16 v[90:91], v2 offset:0x1400
	ds_read_b64_tr_b16 v[92:93], v2 offset:0x1c00
	ds_read_b64_tr_b16 v[94:95], v2 offset:0x2400
	ds_read_b64_tr_b16 v[96:97], v2 offset:0x2c00
	ds_read_b64_tr_b16 v[98:99], v2 offset:0x3400
	ds_read_b64_tr_b16 v[100:101], v2 offset:0x3c00
	s_waitcnt lgkmcnt(8)
	v_mfma_f32_32x32x16_f16 v[50:65], v[4:7], v[102:105], v[50:65]
	v_mfma_f32_32x32x16_f16 v[50:65], v[8:11], v[106:109], v[50:65]
	v_mfma_f32_32x32x16_f16 v[50:65], v[12:15], v[110:113], v[50:65]
	v_mfma_f32_32x32x16_f16 v[50:65], v[82:85], v[190:193], v[50:65]
	ds_read_b64_tr_b16 v[102:103], v2 offset:0x600
	ds_read_b64_tr_b16 v[104:105], v2 offset:0xe00
	ds_read_b64_tr_b16 v[106:107], v2 offset:0x1600
	ds_read_b64_tr_b16 v[108:109], v2 offset:0x1e00
	ds_read_b64_tr_b16 v[110:111], v2 offset:0x2600
	ds_read_b64_tr_b16 v[112:113], v2 offset:0x2e00
	ds_read_b64_tr_b16 v[192:193], v2 offset:0x3600
	ds_read_b64_tr_b16 v[194:195], v2 offset:0x3e00
	s_waitcnt lgkmcnt(8)
	v_mfma_f32_32x32x16_f16 v[34:49], v[4:7], v[86:89], v[34:49]
	v_mfma_f32_32x32x16_f16 v[34:49], v[8:11], v[90:93], v[34:49]
	v_mfma_f32_32x32x16_f16 v[34:49], v[12:15], v[94:97], v[34:49]
	v_mfma_f32_32x32x16_f16 v[34:49], v[82:85], v[98:101], v[34:49]
	s_waitcnt lgkmcnt(0)
	v_mfma_f32_32x32x16_f16 v[18:33], v[4:7], v[102:105], v[18:33]
	v_mov_b32_e32 v190, v196
	v_mfma_f32_32x32x16_f16 v[18:33], v[8:11], v[106:109], v[18:33]
	v_mfma_f32_32x32x16_f16 v[18:33], v[12:15], v[110:113], v[18:33]
	v_mfma_f32_32x32x16_f16 v[18:33], v[82:85], v[192:195], v[18:33]

; #define FA_SBAR() __builtin_amdgcn_sched_barrier(0)
; #define FA_RD8(S, d0) do { constexpr int b_ = v_rd_off(d0, 0, 0); FA_TRRD(S##l0, b_); FA_TRRD(S##h0, b_ + 2048); FA_TRRD(S##l1, b_ + 4096); FA_TRRD(S##h1, b_ + 6144); FA_TRRD(S##l2, b_ + 8192); FA_TRRD(S##h2, b_ + 10240); FA_TRRD(S##l3, b_ + 12288); FA_TRRD(S##h3, b_ + 14336); } while (0)
; __device__ __forceinline__ void partialSM(f32x16& p0, f32x16& p1, float& m_reg, float& mn, float& alpha, const float sc, const float C2) {
;     ...
;     const float mnL = -mn * C2;
; #pragma unroll
;     for (int r = 0; r < 16; ++r) p0[r] = __builtin_amdgcn_exp2f(fmaf(p0[r], C2, mnL));
; #pragma unroll
;     for (int r = 0; r < 16; ++r) p1[r] = __builtin_amdgcn_exp2f(fmaf(p1[r], C2, mnL));
; }
; __device__ __forceinline__ void finishSM(const f32x16& p0, const f32x16& p1, float alpha, float& l_reg, half8& pa0, half8& pa1, half8& pa2, half8& pa3) {
;     f32x2 s2 = {0.f, 0.f};
; #pragma unroll
;     for (int r = 0; r < 16; r += 2) { s2 += (f32x2){p0[r], p0[r + 1]}; s2 += (f32x2){p1[r], p1[r + 1]}; }
;     float ps = s2[0] + s2[1];
;     { auto rr = __builtin_amdgcn_permlane32_swap(__float_as_uint(ps), __float_as_uint(ps), false, false);
;       ps = __uint_as_float(rr[0]) + __uint_as_float(rr[1]); }
;     l_reg = l_reg * alpha + ps;
;     ...
;     FA_PK4(p0, 0, pa0); FA_PK4(p0, 8, pa1); FA_PK4(p1, 0, pa2); FA_PK4(p1, 8, pa3);
; __device__ __forceinline__ void pv_tile2(f32x16* o, int vb0, half8 pa0, half8 pa1, half8 pa2, half8 pa3) {
;     ...
;     s16x4 al0, al1, al2, al3, ah0, ah1, ah2, ah3, bl0, bl1, bl2, bl3, bh0, bh1, bh2, bh3;
;     FA_RD8(a, 0);
;     FA_RD8(b, 1); asm volatile("s_waitcnt lgkmcnt(8)" ::: "memory"); FA_SBAR(); FA_MM4(a, 0); FA_SBAR();
;     FA_RD8(a, 2); asm volatile("s_waitcnt lgkmcnt(8)" ::: "memory"); FA_SBAR(); FA_MM4(b, 1); FA_SBAR();
;     FA_RD8(b, 3); asm volatile("s_waitcnt lgkmcnt(8)" ::: "memory"); FA_SBAR(); FA_MM4(a, 2); FA_SBAR();
;     asm volatile("s_waitcnt lgkmcnt(0)" ::: "memory"); FA_SBAR(); FA_MM4(b, 3);
.Lwin_fast:
.LBB0_5015:
	v_mul_f32_e32 v5, 0xbe0293ee, v182
	v_fmamk_f32 v6, v98, 0x3e0293ee, v5
	v_fmamk_f32 v7, v99, 0x3e0293ee, v5
	v_exp_f32_e32 v6, v6
	v_exp_f32_e32 v7, v7
	v_fmamk_f32 v82, v82, 0x3e0293ee, v5
	v_fmamk_f32 v83, v83, 0x3e0293ee, v5
	v_fmamk_f32 v8, v100, 0x3e0293ee, v5
	v_fmamk_f32 v9, v101, 0x3e0293ee, v5
	v_exp_f32_e32 v82, v82
	v_exp_f32_e32 v83, v83
	v_exp_f32_e32 v8, v8
	v_exp_f32_e32 v9, v9
	v_fmamk_f32 v84, v84, 0x3e0293ee, v5
	v_fmamk_f32 v85, v85, 0x3e0293ee, v5
	v_fmamk_f32 v10, v102, 0x3e0293ee, v5
	v_fmamk_f32 v11, v103, 0x3e0293ee, v5
	v_exp_f32_e32 v84, v84
	v_exp_f32_e32 v85, v85
	v_exp_f32_e32 v10, v10
	v_exp_f32_e32 v11, v11
	v_fmamk_f32 v86, v86, 0x3e0293ee, v5
	v_fmamk_f32 v87, v87, 0x3e0293ee, v5
	v_pk_add_f32 v[102:103], v[6:7], 0 op_sel_hi:[1,0]
	v_fmamk_f32 v12, v104, 0x3e0293ee, v5
	v_fmamk_f32 v13, v105, 0x3e0293ee, v5
	v_exp_f32_e32 v86, v86
	v_exp_f32_e32 v87, v87
	v_pk_add_f32 v[102:103], v[82:83], v[102:103]
	v_exp_f32_e32 v12, v12
	v_exp_f32_e32 v13, v13
	v_fmamk_f32 v88, v88, 0x3e0293ee, v5
	v_fmamk_f32 v89, v89, 0x3e0293ee, v5
	v_pk_add_f32 v[102:103], v[8:9], v[102:103]
	v_fmamk_f32 v14, v106, 0x3e0293ee, v5
	v_fmamk_f32 v15, v107, 0x3e0293ee, v5
	v_exp_f32_e32 v88, v88
	v_exp_f32_e32 v89, v89
	v_pk_add_f32 v[102:103], v[84:85], v[102:103]
	v_exp_f32_e32 v14, v14
	v_exp_f32_e32 v15, v15
	v_fmamk_f32 v90, v90, 0x3e0293ee, v5
	v_fmamk_f32 v91, v91, 0x3e0293ee, v5
	v_pk_add_f32 v[102:103], v[10:11], v[102:103]
	v_fmamk_f32 v16, v108, 0x3e0293ee, v5
	v_fmamk_f32 v17, v109, 0x3e0293ee, v5
	v_exp_f32_e32 v90, v90
	v_exp_f32_e32 v91, v91
	v_pk_add_f32 v[102:103], v[86:87], v[102:103]
	v_exp_f32_e32 v16, v16
	v_exp_f32_e32 v17, v17
	v_fmamk_f32 v92, v92, 0x3e0293ee, v5
	v_fmamk_f32 v93, v93, 0x3e0293ee, v5
	v_pk_add_f32 v[102:103], v[12:13], v[102:103]
	v_fmamk_f32 v98, v110, 0x3e0293ee, v5
	v_fmamk_f32 v99, v111, 0x3e0293ee, v5
	v_exp_f32_e32 v92, v92
	v_exp_f32_e32 v93, v93
	v_pk_add_f32 v[102:103], v[88:89], v[102:103]
	v_exp_f32_e32 v98, v98
	v_exp_f32_e32 v99, v99
	v_fmamk_f32 v94, v94, 0x3e0293ee, v5
	v_fmamk_f32 v95, v95, 0x3e0293ee, v5
	v_pk_add_f32 v[102:103], v[14:15], v[102:103]
	v_fmamk_f32 v100, v112, 0x3e0293ee, v5
	v_fmamk_f32 v101, v113, 0x3e0293ee, v5
	v_exp_f32_e32 v94, v94
	v_exp_f32_e32 v95, v95
	v_pk_add_f32 v[102:103], v[90:91], v[102:103]
	v_exp_f32_e32 v100, v100
	v_exp_f32_e32 v101, v101
	v_fmamk_f32 v96, v96, 0x3e0293ee, v5
	v_fmac_f32_e32 v5, 0x3e0293ee, v97
	v_pk_add_f32 v[102:103], v[16:17], v[102:103]
	v_exp_f32_e32 v96, v96
	v_exp_f32_e32 v97, v5
	v_pk_add_f32 v[102:103], v[92:93], v[102:103]
	v_cvt_pk_f16_f32 v4, v6, v7
	v_pk_add_f32 v[102:103], v[98:99], v[102:103]
	v_cvt_pk_f16_f32 v5, v8, v9
	v_pk_add_f32 v[102:103], v[94:95], v[102:103]
	v_cvt_pk_f16_f32 v6, v10, v11
	v_pk_add_f32 v[102:103], v[100:101], v[102:103]
	v_cvt_pk_f16_f32 v7, v12, v13
	v_pk_add_f32 v[102:103], v[96:97], v[102:103]
	v_cvt_pk_f16_f32 v8, v14, v15
	v_pk_add_f32 v[102:103], v[102:103], v[102:103] op_sel:[0,1] op_sel_hi:[1,0]
	v_cvt_pk_f16_f32 v9, v16, v17
	v_mov_b32_e32 v103, v102
	v_cvt_pk_f16_f32 v10, v98, v99
	v_cvt_pk_f16_f32 v11, v100, v101
	v_permlane32_swap_b32_e32 v102, v103
	v_cvt_pk_f16_f32 v12, v82, v83
	v_add_f32_e32 v103, v102, v103
	v_cvt_pk_f16_f32 v13, v84, v85
	v_fma_f32 v183, v183, v188, v103
	v_cvt_pk_f16_f32 v14, v86, v87
	v_cvt_pk_f16_f32 v15, v88, v89
	v_cvt_pk_f16_f32 v82, v90, v91
	v_cvt_pk_f16_f32 v83, v92, v93
	v_cvt_pk_f16_f32 v84, v94, v95
	v_cvt_pk_f16_f32 v85, v96, v97
	v_permlane32_swap_b32_e32 v4, v6
	v_permlane32_swap_b32_e32 v5, v7
	v_permlane32_swap_b32_e32 v8, v10
	v_permlane32_swap_b32_e32 v9, v11
	v_permlane32_swap_b32_e32 v12, v14
	v_permlane32_swap_b32_e32 v13, v15
	v_permlane32_swap_b32_e32 v82, v84
	v_permlane32_swap_b32_e32 v83, v85
	v_add_u32_e32 v2, v180, v2
	ds_read_b64_tr_b16 v[86:87], v2 offset:0
	ds_read_b64_tr_b16 v[88:89], v2 offset:0x800
	ds_read_b64_tr_b16 v[90:91], v2 offset:0x1000
	ds_read_b64_tr_b16 v[92:93], v2 offset:0x1800
	ds_read_b64_tr_b16 v[94:95], v2 offset:0x2000
	ds_read_b64_tr_b16 v[96:97], v2 offset:0x2800
	ds_read_b64_tr_b16 v[98:99], v2 offset:0x3000
	ds_read_b64_tr_b16 v[100:101], v2 offset:0x3800
	ds_read_b64_tr_b16 v[102:103], v2 offset:0x200
	ds_read_b64_tr_b16 v[104:105], v2 offset:0xa00
	ds_read_b64_tr_b16 v[106:107], v2 offset:0x1200
	ds_read_b64_tr_b16 v[108:109], v2 offset:0x1a00
	ds_read_b64_tr_b16 v[110:111], v2 offset:0x2200
	ds_read_b64_tr_b16 v[112:113], v2 offset:0x2a00
	ds_read_b64_tr_b16 v[184:185], v2 offset:0x3200
	ds_read_b64_tr_b16 v[186:187], v2 offset:0x3a00
	s_waitcnt lgkmcnt(14)
	s_nop 0
	v_mfma_f32_32x32x16_f16 v[66:81], v[4:7], v[86:89], v[66:81]
	s_waitcnt lgkmcnt(12)
	v_mfma_f32_32x32x16_f16 v[66:81], v[8:11], v[90:93], v[66:81]
	s_waitcnt lgkmcnt(10)
	v_mfma_f32_32x32x16_f16 v[66:81], v[12:15], v[94:97], v[66:81]
	s_waitcnt lgkmcnt(8)
	v_mfma_f32_32x32x16_f16 v[66:81], v[82:85], v[98:101], v[66:81]
	ds_read_b64_tr_b16 v[86:87], v2 offset:0x400
	ds_read_b64_tr_b16 v[88:89], v2 offset:0xc00
	ds_read_b64_tr_b16 v[90:91], v2 offset:0x1400
	ds_read_b64_tr_b16 v[92:93], v2 offset:0x1c00
	ds_read_b64_tr_b16 v[94:95], v2 offset:0x2400
	ds_read_b64_tr_b16 v[96:97], v2 offset:0x2c00
	ds_read_b64_tr_b16 v[98:99], v2 offset:0x3400
	ds_read_b64_tr_b16 v[100:101], v2 offset:0x3c00
	s_waitcnt lgkmcnt(8)
	v_mfma_f32_32x32x16_f16 v[50:65], v[4:7], v[102:105], v[50:65]
	v_mfma_f32_32x32x16_f16 v[50:65], v[8:11], v[106:109], v[50:65]
	v_mfma_f32_32x32x16_f16 v[50:65], v[12:15], v[110:113], v[50:65]
	v_mfma_f32_32x32x16_f16 v[50:65], v[82:85], v[184:187], v[50:65]
	ds_read_b64_tr_b16 v[102:103], v2 offset:0x600
	ds_read_b64_tr_b16 v[104:105], v2 offset:0xe00
	ds_read_b64_tr_b16 v[106:107], v2 offset:0x1600
	ds_read_b64_tr_b16 v[108:109], v2 offset:0x1e00
	ds_read_b64_tr_b16 v[110:111], v2 offset:0x2600
	ds_read_b64_tr_b16 v[112:113], v2 offset:0x2e00
	ds_read_b64_tr_b16 v[184:185], v2 offset:0x3600
	ds_read_b64_tr_b16 v[186:187], v2 offset:0x3e00
	s_waitcnt lgkmcnt(8)
	v_mfma_f32_32x32x16_f16 v[34:49], v[4:7], v[86:89], v[34:49]
	v_mfma_f32_32x32x16_f16 v[34:49], v[8:11], v[90:93], v[34:49]
	v_mfma_f32_32x32x16_f16 v[34:49], v[12:15], v[94:97], v[34:49]
	v_mfma_f32_32x32x16_f16 v[34:49], v[82:85], v[98:101], v[34:49]
	s_waitcnt lgkmcnt(0)
	v_mfma_f32_32x32x16_f16 v[18:33], v[4:7], v[102:105], v[18:33]
	v_mfma_f32_32x32x16_f16 v[18:33], v[8:11], v[106:109], v[18:33]
	v_mfma_f32_32x32x16_f16 v[18:33], v[12:15], v[110:113], v[18:33]
	v_mfma_f32_32x32x16_f16 v[18:33], v[82:85], v[184:187], v[18:33]
